# block layout permutation made relative to the workspace base (no alignment assumption)
# baseline (speedup 1.0000x reference)
.LBB0_2001:
	s_waitcnt lgkmcnt(0)
	v_cndmask_b32_e64 v202, 1.0, v218, s[12:13]
	s_add_i32 s53, s80, -4
	s_mul_hi_u32 s51, s53, 0x900000
	s_mul_i32 s53, s53, 0x900000
	s_ashr_i32 s58, s58, 6
	v_pk_mul_f32 v[146:147], v[202:203], v[146:147] op_sel_hi:[0,1]
	v_pk_mul_f32 v[144:145], v[202:203], v[144:145] op_sel_hi:[0,1]
	v_pk_mul_f32 v[148:149], v[202:203], v[154:155] op_sel_hi:[0,1]
	v_pk_mul_f32 v[150:151], v[202:203], v[152:153] op_sel_hi:[0,1]
	s_mov_b64 s[12:13], -1
	s_and_b64 vcc, exec, s[84:85]
	s_cbranch_vccz .LBB0_2013
	s_mov_b64 s[86:87], -1
	s_mov_b64 s[12:13], 0
	s_cmp_lt_i32 s80, 7
	s_mov_b64 s[82:83], 0
	s_cbranch_scc1 .LBB0_2008
	s_cmp_eq_u32 s80, 7
	s_mov_b64 s[82:83], -1
	s_cbranch_scc0 .LBB0_2005
	v_mov_b32_e32 v154, 0
	v_cvt_pk_fp8_f32 v154, v144, v145
	v_mov_b32_e32 v155, 0
	v_cvt_pk_fp8_f32 v155, v150, v151
	s_add_i32 s60, s58, s30
	v_cvt_pk_fp8_f32 v154, v146, v147 op_sel:[0,0,1]
	s_ashr_i32 s61, s60, 31
	v_cvt_pk_fp8_f32 v155, v148, v149 op_sel:[0,0,1]
	s_lshl_b64 s[60:61], s[60:61], 12
	v_lshl_add_u64 v[152:153], v[178:179], 0, s[60:61]
	v_subrev_u32_e32 v152, s38, v152
	v_lshrrev_b32_e32 v252, 2, v152
	v_lshlrev_b32_e32 v253, 4, v152
	v_and_b32_e32 v252, 0xf0, v252
	v_and_b32_e32 v253, 0x300, v253
	v_and_b32_e32 v152, 0xfffffc0f, v152
	v_or3_b32 v152, v152, v252, v253
	v_add_u32_e32 v152, s38, v152
	v_lshrrev_b32_e32 v156, 8, v154
	global_store_byte v[152:153], v154, off
	global_store_byte v[152:153], v156, off offset:16
	global_store_byte_d16_hi v[152:153], v154, off offset:32
	v_lshrrev_b32_e32 v154, 24, v154
	global_store_byte v[152:153], v154, off offset:48
	global_store_byte v[152:153], v155, off offset:64
	v_lshrrev_b32_e32 v154, 8, v155
	global_store_byte v[152:153], v154, off offset:80
	global_store_byte_d16_hi v[152:153], v155, off offset:96
	v_lshrrev_b32_e32 v154, 24, v155
	global_store_byte v[152:153], v154, off offset:112
	s_mov_b64 s[82:83], 0

.LBB0_2011:
	v_mov_b32_e32 v154, 0
	v_mov_b32_e32 v155, 0
	v_cvt_pk_fp8_f32 v154, v144, v145
	v_cvt_pk_fp8_f32 v155, v150, v151
	v_lshlrev_b64 v[152:153], 6, v[152:153]
	v_lshl_add_u64 v[152:153], v[180:181], 0, v[152:153]
	v_cvt_pk_fp8_f32 v154, v146, v147 op_sel:[0,0,1]
	v_cvt_pk_fp8_f32 v155, v148, v149 op_sel:[0,0,1]
	v_subrev_u32_e32 v152, s38, v152
	v_lshrrev_b32_e32 v252, 2, v152
	v_lshlrev_b32_e32 v253, 4, v152
	v_and_b32_e32 v252, 0xf0, v252
	v_and_b32_e32 v253, 0x300, v253
	v_and_b32_e32 v152, 0xfffffc0f, v152
	v_or3_b32 v152, v152, v252, v253
	v_add_u32_e32 v152, s38, v152
	global_store_dwordx2 v[152:153], v[154:155], off sc1

.LBB0_2023:
	s_waitcnt vmcnt(0)
	v_mov_b32_e32 v128, v202
	v_mov_b32_e32 v129, v202
	v_mov_b32_e32 v203, v202
	v_pk_mul_f32 v[126:127], v[128:129], v[126:127]
	v_pk_mul_f32 v[122:123], v[128:129], v[122:123]
	v_cndmask_b32_e64 v128, 0, 1, s[84:85]
	v_pk_mul_f32 v[124:125], v[202:203], v[124:125]
	v_pk_mul_f32 v[120:121], v[202:203], v[120:121]
	v_cmp_ne_u32_e64 s[12:13], 1, v128
	s_andn2_b64 vcc, exec, s[84:85]
	s_mov_b64 s[84:85], -1
	s_cbranch_vccnz .LBB0_2030
	s_mov_b64 s[88:89], -1
	s_mov_b64 s[84:85], 0
	s_cmp_lt_i32 s80, 7
	s_mov_b64 s[86:87], 0
	s_cbranch_scc1 .LBB0_2033
	s_cmp_eq_u32 s80, 7
	s_mov_b64 s[86:87], -1
	s_cbranch_scc0 .LBB0_2027
	v_mov_b32_e32 v130, v171
	v_cvt_pk_fp8_f32 v130, v124, v125
	v_mov_b32_e32 v131, v171
	v_cvt_pk_fp8_f32 v131, v120, v121
	s_add_i32 s60, s58, s33
	v_cvt_pk_fp8_f32 v130, v126, v127 op_sel:[0,0,1]
	s_ashr_i32 s61, s60, 31
	v_cvt_pk_fp8_f32 v131, v122, v123 op_sel:[0,0,1]
	s_lshl_b64 s[60:61], s[60:61], 12
	v_lshl_add_u64 v[128:129], v[182:183], 0, s[60:61]
	v_subrev_u32_e32 v128, s38, v128
	v_lshrrev_b32_e32 v252, 2, v128
	v_lshlrev_b32_e32 v253, 4, v128
	v_and_b32_e32 v252, 0xf0, v252
	v_and_b32_e32 v253, 0x300, v253
	v_and_b32_e32 v128, 0xfffffc0f, v128
	v_or3_b32 v128, v128, v252, v253
	v_add_u32_e32 v128, s38, v128
	v_lshrrev_b32_e32 v132, 8, v130
	global_store_byte v[128:129], v130, off
	global_store_byte v[128:129], v132, off offset:16
	global_store_byte_d16_hi v[128:129], v130, off offset:32
	v_lshrrev_b32_e32 v130, 24, v130
	global_store_byte v[128:129], v130, off offset:48
	global_store_byte v[128:129], v131, off offset:64
	v_lshrrev_b32_e32 v130, 8, v131
	global_store_byte v[128:129], v130, off offset:80
	global_store_byte_d16_hi v[128:129], v131, off offset:96
	v_lshrrev_b32_e32 v130, 24, v131
	global_store_byte v[128:129], v130, off offset:112
	s_mov_b64 s[86:87], 0

.LBB0_2036:
	v_mov_b32_e32 v130, v171
	v_mov_b32_e32 v131, v171
	v_cvt_pk_fp8_f32 v130, v124, v125
	v_cvt_pk_fp8_f32 v131, v120, v121
	v_lshlrev_b64 v[128:129], 6, v[128:129]
	v_lshl_add_u64 v[128:129], v[184:185], 0, v[128:129]
	v_cvt_pk_fp8_f32 v130, v126, v127 op_sel:[0,0,1]
	v_cvt_pk_fp8_f32 v131, v122, v123 op_sel:[0,0,1]
	v_subrev_u32_e32 v128, s38, v128
	v_lshrrev_b32_e32 v252, 2, v128
	v_lshlrev_b32_e32 v253, 4, v128
	v_and_b32_e32 v252, 0xf0, v252
	v_and_b32_e32 v253, 0x300, v253
	v_and_b32_e32 v128, 0xfffffc0f, v128
	v_or3_b32 v128, v128, v252, v253
	v_add_u32_e32 v128, s38, v128
	global_store_dwordx2 v[128:129], v[130:131], off sc1

.LBB0_2048:
	s_waitcnt lgkmcnt(6)
	v_mov_b32_e32 v140, v202
	s_waitcnt lgkmcnt(4)
	v_mov_b32_e32 v141, v202
	v_pk_mul_f32 v[138:139], v[140:141], v[138:139]
	v_pk_mul_f32 v[136:137], v[202:203], v[136:137]
	v_pk_mul_f32 v[140:141], v[140:141], v[146:147]
	v_pk_mul_f32 v[142:143], v[202:203], v[144:145]
	s_and_b64 vcc, exec, s[12:13]
	s_mov_b64 s[84:85], -1
	s_cbranch_vccnz .LBB0_2060
	s_mov_b64 s[88:89], -1
	s_mov_b64 s[84:85], 0
	s_cmp_lt_i32 s80, 7
	s_mov_b64 s[86:87], 0
	s_cbranch_scc1 .LBB0_2055
	s_cmp_eq_u32 s80, 7
	s_mov_b64 s[86:87], -1
	s_cbranch_scc0 .LBB0_2052
	v_mov_b32_e32 v146, v171
	v_cvt_pk_fp8_f32 v146, v136, v137
	v_mov_b32_e32 v147, v171
	v_cvt_pk_fp8_f32 v147, v142, v143
	s_add_i32 s60, s58, s30
	v_cvt_pk_fp8_f32 v146, v138, v139 op_sel:[0,0,1]
	s_ashr_i32 s61, s60, 31
	v_cvt_pk_fp8_f32 v147, v140, v141 op_sel:[0,0,1]
	s_lshl_b64 s[60:61], s[60:61], 12
	v_lshl_add_u64 v[144:145], v[178:179], 0, s[60:61]
	v_subrev_u32_e32 v144, s38, v144
	v_lshrrev_b32_e32 v252, 2, v144
	v_lshlrev_b32_e32 v253, 4, v144
	v_and_b32_e32 v252, 0xf0, v252
	v_and_b32_e32 v253, 0x300, v253
	v_and_b32_e32 v144, 0xfffffc0f, v144
	v_or3_b32 v144, v144, v252, v253
	v_add_u32_e32 v144, s38, v144
	v_lshrrev_b32_e32 v148, 8, v146
	global_store_byte v[144:145], v146, off offset:4
	global_store_byte v[144:145], v148, off offset:20
	global_store_byte_d16_hi v[144:145], v146, off offset:36
	v_lshrrev_b32_e32 v146, 24, v146
	global_store_byte v[144:145], v146, off offset:52
	global_store_byte v[144:145], v147, off offset:68
	v_lshrrev_b32_e32 v146, 8, v147
	global_store_byte v[144:145], v146, off offset:84
	global_store_byte_d16_hi v[144:145], v147, off offset:100
	v_lshrrev_b32_e32 v146, 24, v147
	global_store_byte v[144:145], v146, off offset:116
	s_mov_b64 s[86:87], 0

.LBB0_2058:
	v_mov_b32_e32 v146, v171
	v_mov_b32_e32 v147, v171
	v_cvt_pk_fp8_f32 v146, v136, v137
	v_cvt_pk_fp8_f32 v147, v142, v143
	v_lshlrev_b64 v[144:145], 6, v[144:145]
	v_lshl_add_u64 v[144:145], v[180:181], 0, v[144:145]
	v_cvt_pk_fp8_f32 v146, v138, v139 op_sel:[0,0,1]
	v_cvt_pk_fp8_f32 v147, v140, v141 op_sel:[0,0,1]
	v_subrev_u32_e32 v144, s38, v144
	v_lshrrev_b32_e32 v252, 2, v144
	v_lshlrev_b32_e32 v253, 4, v144
	v_and_b32_e32 v252, 0xf0, v252
	v_and_b32_e32 v253, 0x300, v253
	v_and_b32_e32 v144, 0xfffffc0f, v144
	v_or3_b32 v144, v144, v252, v253
	v_add_u32_e32 v144, s38, v144
	global_store_dwordx2 v[144:145], v[146:147], off sc1

.LBB0_2070:
	s_waitcnt vmcnt(3)
	v_mov_b32_e32 v120, v202
	v_mov_b32_e32 v121, v202
	v_pk_mul_f32 v[118:119], v[120:121], v[118:119]
	v_pk_mul_f32 v[116:117], v[202:203], v[116:117]
	v_pk_mul_f32 v[114:115], v[120:121], v[114:115]
	v_pk_mul_f32 v[112:113], v[202:203], v[112:113]
	s_and_b64 vcc, exec, s[12:13]
	s_mov_b64 s[84:85], -1
	s_cbranch_vccnz .LBB0_2077
	s_mov_b64 s[88:89], -1
	s_mov_b64 s[84:85], 0
	s_cmp_lt_i32 s80, 7
	s_mov_b64 s[86:87], 0
	s_cbranch_scc1 .LBB0_2080
	s_cmp_eq_u32 s80, 7
	s_mov_b64 s[86:87], -1
	s_cbranch_scc0 .LBB0_2074
	v_mov_b32_e32 v122, v171
	v_cvt_pk_fp8_f32 v122, v116, v117
	v_mov_b32_e32 v123, v171
	v_cvt_pk_fp8_f32 v123, v112, v113
	s_add_i32 s60, s58, s33
	v_cvt_pk_fp8_f32 v122, v118, v119 op_sel:[0,0,1]
	s_ashr_i32 s61, s60, 31
	v_cvt_pk_fp8_f32 v123, v114, v115 op_sel:[0,0,1]
	s_lshl_b64 s[60:61], s[60:61], 12
	v_lshl_add_u64 v[120:121], v[182:183], 0, s[60:61]
	v_subrev_u32_e32 v120, s38, v120
	v_lshrrev_b32_e32 v252, 2, v120
	v_lshlrev_b32_e32 v253, 4, v120
	v_and_b32_e32 v252, 0xf0, v252
	v_and_b32_e32 v253, 0x300, v253
	v_and_b32_e32 v120, 0xfffffc0f, v120
	v_or3_b32 v120, v120, v252, v253
	v_add_u32_e32 v120, s38, v120
	s_waitcnt vmcnt(1)
	v_lshrrev_b32_e32 v124, 8, v122
	global_store_byte v[120:121], v122, off offset:4
	global_store_byte v[120:121], v124, off offset:20
	global_store_byte_d16_hi v[120:121], v122, off offset:36
	v_lshrrev_b32_e32 v122, 24, v122
	global_store_byte v[120:121], v122, off offset:52
	global_store_byte v[120:121], v123, off offset:68
	v_lshrrev_b32_e32 v122, 8, v123
	global_store_byte v[120:121], v122, off offset:84
	global_store_byte_d16_hi v[120:121], v123, off offset:100
	v_lshrrev_b32_e32 v122, 24, v123
	global_store_byte v[120:121], v122, off offset:116
	s_mov_b64 s[86:87], 0

.LBB0_2083:
	v_mov_b32_e32 v122, v171
	v_mov_b32_e32 v123, v171
	v_cvt_pk_fp8_f32 v122, v116, v117
	v_cvt_pk_fp8_f32 v123, v112, v113
	v_lshlrev_b64 v[120:121], 6, v[120:121]
	v_lshl_add_u64 v[120:121], v[184:185], 0, v[120:121]
	v_cvt_pk_fp8_f32 v122, v118, v119 op_sel:[0,0,1]
	v_cvt_pk_fp8_f32 v123, v114, v115 op_sel:[0,0,1]
	v_subrev_u32_e32 v120, s38, v120
	v_lshrrev_b32_e32 v252, 2, v120
	v_lshlrev_b32_e32 v253, 4, v120
	v_and_b32_e32 v252, 0xf0, v252
	v_and_b32_e32 v253, 0x300, v253
	v_and_b32_e32 v120, 0xfffffc0f, v120
	v_or3_b32 v120, v120, v252, v253
	v_add_u32_e32 v120, s38, v120
	global_store_dwordx2 v[120:121], v[122:123], off sc1

.LBB0_2095:
	s_waitcnt vmcnt(0) lgkmcnt(6)
	v_mov_b32_e32 v132, v202
	s_waitcnt lgkmcnt(4)
	v_mov_b32_e32 v133, v202
	v_pk_mul_f32 v[130:131], v[132:133], v[130:131]
	v_pk_mul_f32 v[128:129], v[202:203], v[128:129]
	v_pk_mul_f32 v[132:133], v[132:133], v[138:139]
	v_pk_mul_f32 v[134:135], v[202:203], v[136:137]
	s_and_b64 vcc, exec, s[12:13]
	s_mov_b64 s[84:85], -1
	s_cbranch_vccnz .LBB0_2107
	s_mov_b64 s[88:89], -1
	s_mov_b64 s[84:85], 0
	s_cmp_lt_i32 s80, 7
	s_mov_b64 s[86:87], 0
	s_cbranch_scc1 .LBB0_2102
	s_cmp_eq_u32 s80, 7
	s_mov_b64 s[86:87], -1
	s_cbranch_scc0 .LBB0_2099
	v_mov_b32_e32 v138, v171
	v_cvt_pk_fp8_f32 v138, v128, v129
	v_mov_b32_e32 v139, v171
	v_cvt_pk_fp8_f32 v139, v134, v135
	s_add_i32 s60, s58, s30
	v_cvt_pk_fp8_f32 v138, v130, v131 op_sel:[0,0,1]
	s_ashr_i32 s61, s60, 31
	v_cvt_pk_fp8_f32 v139, v132, v133 op_sel:[0,0,1]
	s_lshl_b64 s[60:61], s[60:61], 12
	v_lshl_add_u64 v[136:137], v[178:179], 0, s[60:61]
	v_subrev_u32_e32 v136, s38, v136
	v_lshrrev_b32_e32 v252, 2, v136
	v_lshlrev_b32_e32 v253, 4, v136
	v_and_b32_e32 v252, 0xf0, v252
	v_and_b32_e32 v253, 0x300, v253
	v_and_b32_e32 v136, 0xfffffc0f, v136
	v_or3_b32 v136, v136, v252, v253
	v_add_u32_e32 v136, s38, v136
	v_lshrrev_b32_e32 v140, 8, v138
	global_store_byte v[136:137], v138, off offset:8
	global_store_byte v[136:137], v140, off offset:24
	global_store_byte_d16_hi v[136:137], v138, off offset:40
	v_lshrrev_b32_e32 v138, 24, v138
	global_store_byte v[136:137], v138, off offset:56
	global_store_byte v[136:137], v139, off offset:72
	v_lshrrev_b32_e32 v138, 8, v139
	global_store_byte v[136:137], v138, off offset:88
	global_store_byte_d16_hi v[136:137], v139, off offset:104
	v_lshrrev_b32_e32 v138, 24, v139
	global_store_byte v[136:137], v138, off offset:120
	s_mov_b64 s[86:87], 0

.LBB0_2105:
	v_mov_b32_e32 v138, v171
	v_mov_b32_e32 v139, v171
	v_cvt_pk_fp8_f32 v138, v128, v129
	v_cvt_pk_fp8_f32 v139, v134, v135
	v_lshlrev_b64 v[136:137], 6, v[136:137]
	v_lshl_add_u64 v[136:137], v[180:181], 0, v[136:137]
	v_cvt_pk_fp8_f32 v138, v130, v131 op_sel:[0,0,1]
	v_cvt_pk_fp8_f32 v139, v132, v133 op_sel:[0,0,1]
	v_subrev_u32_e32 v136, s38, v136
	v_lshrrev_b32_e32 v252, 2, v136
	v_lshlrev_b32_e32 v253, 4, v136
	v_and_b32_e32 v252, 0xf0, v252
	v_and_b32_e32 v253, 0x300, v253
	v_and_b32_e32 v136, 0xfffffc0f, v136
	v_or3_b32 v136, v136, v252, v253
	v_add_u32_e32 v136, s38, v136
	global_store_dwordx2 v[136:137], v[138:139], off sc1

.LBB0_2117:
	v_mov_b32_e32 v112, v202
	v_mov_b32_e32 v113, v202
	v_pk_mul_f32 v[110:111], v[112:113], v[110:111]
	v_pk_mul_f32 v[108:109], v[202:203], v[108:109]
	v_pk_mul_f32 v[106:107], v[112:113], v[106:107]
	v_pk_mul_f32 v[104:105], v[202:203], v[104:105]
	s_and_b64 vcc, exec, s[12:13]
	s_mov_b64 s[84:85], -1
	s_cbranch_vccnz .LBB0_2124
	s_mov_b64 s[88:89], -1
	s_mov_b64 s[84:85], 0
	s_cmp_lt_i32 s80, 7
	s_mov_b64 s[86:87], 0
	s_cbranch_scc1 .LBB0_2127
	s_cmp_eq_u32 s80, 7
	s_mov_b64 s[86:87], -1
	s_cbranch_scc0 .LBB0_2121
	v_mov_b32_e32 v114, v171
	v_cvt_pk_fp8_f32 v114, v108, v109
	v_mov_b32_e32 v115, v171
	v_cvt_pk_fp8_f32 v115, v104, v105
	s_add_i32 s60, s58, s33
	v_cvt_pk_fp8_f32 v114, v110, v111 op_sel:[0,0,1]
	s_ashr_i32 s61, s60, 31
	v_cvt_pk_fp8_f32 v115, v106, v107 op_sel:[0,0,1]
	s_lshl_b64 s[60:61], s[60:61], 12
	v_lshl_add_u64 v[112:113], v[182:183], 0, s[60:61]
	v_subrev_u32_e32 v112, s38, v112
	v_lshrrev_b32_e32 v252, 2, v112
	v_lshlrev_b32_e32 v253, 4, v112
	v_and_b32_e32 v252, 0xf0, v252
	v_and_b32_e32 v253, 0x300, v253
	v_and_b32_e32 v112, 0xfffffc0f, v112
	v_or3_b32 v112, v112, v252, v253
	v_add_u32_e32 v112, s38, v112
	v_lshrrev_b32_e32 v116, 8, v114
	global_store_byte v[112:113], v114, off offset:8
	global_store_byte v[112:113], v116, off offset:24
	global_store_byte_d16_hi v[112:113], v114, off offset:40
	v_lshrrev_b32_e32 v114, 24, v114
	global_store_byte v[112:113], v114, off offset:56
	global_store_byte v[112:113], v115, off offset:72
	v_lshrrev_b32_e32 v114, 8, v115
	global_store_byte v[112:113], v114, off offset:88
	global_store_byte_d16_hi v[112:113], v115, off offset:104
	v_lshrrev_b32_e32 v114, 24, v115
	global_store_byte v[112:113], v114, off offset:120
	s_mov_b64 s[86:87], 0

.LBB0_2130:
	v_mov_b32_e32 v114, v171
	v_mov_b32_e32 v115, v171
	v_cvt_pk_fp8_f32 v114, v108, v109
	v_cvt_pk_fp8_f32 v115, v104, v105
	v_lshlrev_b64 v[112:113], 6, v[112:113]
	v_lshl_add_u64 v[112:113], v[184:185], 0, v[112:113]
	v_cvt_pk_fp8_f32 v114, v110, v111 op_sel:[0,0,1]
	v_cvt_pk_fp8_f32 v115, v106, v107 op_sel:[0,0,1]
	v_subrev_u32_e32 v112, s38, v112
	v_lshrrev_b32_e32 v252, 2, v112
	v_lshlrev_b32_e32 v253, 4, v112
	v_and_b32_e32 v252, 0xf0, v252
	v_and_b32_e32 v253, 0x300, v253
	v_and_b32_e32 v112, 0xfffffc0f, v112
	v_or3_b32 v112, v112, v252, v253
	v_add_u32_e32 v112, s38, v112
	global_store_dwordx2 v[112:113], v[114:115], off sc1

.LBB0_2142:
	s_waitcnt lgkmcnt(6)
	v_mov_b32_e32 v124, v202
	s_waitcnt lgkmcnt(4)
	v_mov_b32_e32 v125, v202
	v_pk_mul_f32 v[122:123], v[124:125], v[122:123]
	v_pk_mul_f32 v[120:121], v[202:203], v[120:121]
	v_pk_mul_f32 v[124:125], v[124:125], v[130:131]
	v_pk_mul_f32 v[126:127], v[202:203], v[128:129]
	s_and_b64 vcc, exec, s[12:13]
	s_mov_b64 s[84:85], -1
	s_cbranch_vccnz .LBB0_2154
	s_mov_b64 s[88:89], -1
	s_mov_b64 s[84:85], 0
	s_cmp_lt_i32 s80, 7
	s_mov_b64 s[86:87], 0
	s_cbranch_scc1 .LBB0_2149
	s_cmp_eq_u32 s80, 7
	s_mov_b64 s[86:87], -1
	s_cbranch_scc0 .LBB0_2146
	v_mov_b32_e32 v130, v171
	v_cvt_pk_fp8_f32 v130, v120, v121
	v_mov_b32_e32 v131, v171
	v_cvt_pk_fp8_f32 v131, v126, v127
	s_add_i32 s60, s58, s30
	v_cvt_pk_fp8_f32 v130, v122, v123 op_sel:[0,0,1]
	s_ashr_i32 s61, s60, 31
	v_cvt_pk_fp8_f32 v131, v124, v125 op_sel:[0,0,1]
	s_lshl_b64 s[60:61], s[60:61], 12
	v_lshl_add_u64 v[128:129], v[186:187], 0, s[60:61]
	v_subrev_u32_e32 v128, s38, v128
	v_lshrrev_b32_e32 v252, 2, v128
	v_lshlrev_b32_e32 v253, 4, v128
	v_and_b32_e32 v252, 0xf0, v252
	v_and_b32_e32 v253, 0x300, v253
	v_and_b32_e32 v128, 0xfffffc0f, v128
	v_or3_b32 v128, v128, v252, v253
	v_add_u32_e32 v128, s38, v128
	v_lshrrev_b32_e32 v132, 8, v130
	global_store_byte v[128:129], v130, off
	global_store_byte v[128:129], v132, off offset:16
	global_store_byte_d16_hi v[128:129], v130, off offset:32
	v_lshrrev_b32_e32 v130, 24, v130
	global_store_byte v[128:129], v130, off offset:48
	global_store_byte v[128:129], v131, off offset:64
	v_lshrrev_b32_e32 v130, 8, v131
	global_store_byte v[128:129], v130, off offset:80
	global_store_byte_d16_hi v[128:129], v131, off offset:96
	v_lshrrev_b32_e32 v130, 24, v131
	global_store_byte v[128:129], v130, off offset:112
	s_mov_b64 s[86:87], 0

.LBB0_2152:
	v_mov_b32_e32 v130, v171
	v_mov_b32_e32 v131, v171
	v_cvt_pk_fp8_f32 v130, v120, v121
	v_cvt_pk_fp8_f32 v131, v126, v127
	v_lshlrev_b64 v[128:129], 6, v[128:129]
	v_lshl_add_u64 v[128:129], v[180:181], 0, v[128:129]
	v_cvt_pk_fp8_f32 v130, v122, v123 op_sel:[0,0,1]
	v_cvt_pk_fp8_f32 v131, v124, v125 op_sel:[0,0,1]
	v_subrev_u32_e32 v128, s38, v128
	v_lshrrev_b32_e32 v252, 2, v128
	v_lshlrev_b32_e32 v253, 4, v128
	v_and_b32_e32 v252, 0xf0, v252
	v_and_b32_e32 v253, 0x300, v253
	v_and_b32_e32 v128, 0xfffffc0f, v128
	v_or3_b32 v128, v128, v252, v253
	v_add_u32_e32 v128, s38, v128
	global_store_dwordx2 v[128:129], v[130:131], off sc1

.LBB0_2164:
	s_waitcnt vmcnt(3)
	v_mov_b32_e32 v104, v202
	v_mov_b32_e32 v105, v202
	v_pk_mul_f32 v[102:103], v[104:105], v[102:103]
	v_pk_mul_f32 v[100:101], v[202:203], v[100:101]
	v_pk_mul_f32 v[98:99], v[104:105], v[98:99]
	v_pk_mul_f32 v[96:97], v[202:203], v[96:97]
	s_and_b64 vcc, exec, s[12:13]
	s_mov_b64 s[84:85], -1
	s_cbranch_vccnz .LBB0_2171
	s_mov_b64 s[88:89], -1
	s_mov_b64 s[84:85], 0
	s_cmp_lt_i32 s80, 7
	s_mov_b64 s[86:87], 0
	s_cbranch_scc1 .LBB0_2174
	s_cmp_eq_u32 s80, 7
	s_mov_b64 s[86:87], -1
	s_cbranch_scc0 .LBB0_2168
	v_mov_b32_e32 v106, v171
	v_cvt_pk_fp8_f32 v106, v100, v101
	v_mov_b32_e32 v107, v171
	v_cvt_pk_fp8_f32 v107, v96, v97
	s_add_i32 s58, s58, s33
	v_cvt_pk_fp8_f32 v106, v102, v103 op_sel:[0,0,1]
	s_ashr_i32 s59, s58, 31
	v_cvt_pk_fp8_f32 v107, v98, v99 op_sel:[0,0,1]
	s_lshl_b64 s[58:59], s[58:59], 12
	v_lshl_add_u64 v[104:105], v[188:189], 0, s[58:59]
	v_subrev_u32_e32 v104, s38, v104
	v_lshrrev_b32_e32 v252, 2, v104
	v_lshlrev_b32_e32 v253, 4, v104
	v_and_b32_e32 v252, 0xf0, v252
	v_and_b32_e32 v253, 0x300, v253
	v_and_b32_e32 v104, 0xfffffc0f, v104
	v_or3_b32 v104, v104, v252, v253
	v_add_u32_e32 v104, s38, v104
	s_waitcnt vmcnt(1)
	v_lshrrev_b32_e32 v108, 8, v106
	global_store_byte v[104:105], v106, off
	global_store_byte v[104:105], v108, off offset:16
	global_store_byte_d16_hi v[104:105], v106, off offset:32
	v_lshrrev_b32_e32 v106, 24, v106
	global_store_byte v[104:105], v106, off offset:48
	global_store_byte v[104:105], v107, off offset:64
	v_lshrrev_b32_e32 v106, 8, v107
	global_store_byte v[104:105], v106, off offset:80
	global_store_byte_d16_hi v[104:105], v107, off offset:96
	v_lshrrev_b32_e32 v106, 24, v107
	global_store_byte v[104:105], v106, off offset:112
	s_mov_b64 s[86:87], 0

.LBB0_2177:
	v_mov_b32_e32 v106, v171
	v_mov_b32_e32 v107, v171
	v_cvt_pk_fp8_f32 v106, v100, v101
	v_cvt_pk_fp8_f32 v107, v96, v97
	v_lshlrev_b64 v[104:105], 6, v[104:105]
	v_lshl_add_u64 v[104:105], v[184:185], 0, v[104:105]
	v_cvt_pk_fp8_f32 v106, v102, v103 op_sel:[0,0,1]
	v_cvt_pk_fp8_f32 v107, v98, v99 op_sel:[0,0,1]
	v_subrev_u32_e32 v104, s38, v104
	v_lshrrev_b32_e32 v252, 2, v104
	v_lshlrev_b32_e32 v253, 4, v104
	v_and_b32_e32 v252, 0xf0, v252
	v_and_b32_e32 v253, 0x300, v253
	v_and_b32_e32 v104, 0xfffffc0f, v104
	v_or3_b32 v104, v104, v252, v253
	v_add_u32_e32 v104, s38, v104
	global_store_dwordx2 v[104:105], v[106:107], off sc1

.LBB0_2189:
	s_waitcnt vmcnt(0) lgkmcnt(6)
	v_mov_b32_e32 v116, v202
	s_waitcnt lgkmcnt(4)
	v_mov_b32_e32 v117, v202
	v_ashrrev_i32_e32 v136, 6, v128
	v_pk_mul_f32 v[114:115], v[116:117], v[114:115]
	v_pk_mul_f32 v[112:113], v[202:203], v[112:113]
	v_pk_mul_f32 v[116:117], v[116:117], v[122:123]
	v_pk_mul_f32 v[118:119], v[202:203], v[120:121]
	s_and_b64 vcc, exec, s[12:13]
	s_mov_b64 s[84:85], -1
	s_cbranch_vccnz .LBB0_2201
	s_mov_b64 s[88:89], -1
	s_mov_b64 s[84:85], 0
	s_cmp_lt_i32 s80, 7
	s_mov_b64 s[86:87], 0
	s_cbranch_scc1 .LBB0_2196
	s_cmp_eq_u32 s80, 7
	s_mov_b64 s[86:87], -1
	s_cbranch_scc0 .LBB0_2193
	v_mov_b32_e32 v122, v171
	v_cvt_pk_fp8_f32 v122, v112, v113
	v_mov_b32_e32 v123, v171
	v_cvt_pk_fp8_f32 v123, v118, v119
	v_add_u32_e32 v120, s30, v136
	v_cvt_pk_fp8_f32 v122, v114, v115 op_sel:[0,0,1]
	v_ashrrev_i32_e32 v121, 31, v120
	v_cvt_pk_fp8_f32 v123, v116, v117 op_sel:[0,0,1]
	v_lshlrev_b64 v[120:121], 12, v[120:121]
	v_lshl_add_u64 v[120:121], v[178:179], 0, v[120:121]
	v_subrev_u32_e32 v120, s38, v120
	v_lshrrev_b32_e32 v252, 2, v120
	v_lshlrev_b32_e32 v253, 4, v120
	v_and_b32_e32 v252, 0xf0, v252
	v_and_b32_e32 v253, 0x300, v253
	v_and_b32_e32 v120, 0xfffffc0f, v120
	v_or3_b32 v120, v120, v252, v253
	v_add_u32_e32 v120, s38, v120
	v_lshrrev_b32_e32 v124, 8, v122
	global_store_byte v[120:121], v122, off
	global_store_byte v[120:121], v124, off offset:16
	global_store_byte_d16_hi v[120:121], v122, off offset:32
	v_lshrrev_b32_e32 v122, 24, v122
	global_store_byte v[120:121], v122, off offset:48
	global_store_byte v[120:121], v123, off offset:64
	v_lshrrev_b32_e32 v122, 8, v123
	global_store_byte v[120:121], v122, off offset:80
	global_store_byte_d16_hi v[120:121], v123, off offset:96
	v_lshrrev_b32_e32 v122, 24, v123
	global_store_byte v[120:121], v122, off offset:112
	s_mov_b64 s[86:87], 0

.LBB0_2199:
	v_mov_b32_e32 v122, v171
	v_mov_b32_e32 v123, v171
	v_cvt_pk_fp8_f32 v122, v112, v113
	v_cvt_pk_fp8_f32 v123, v118, v119
	v_lshlrev_b64 v[120:121], 6, v[120:121]
	v_lshl_add_u64 v[120:121], v[180:181], 0, v[120:121]
	v_cvt_pk_fp8_f32 v122, v114, v115 op_sel:[0,0,1]
	v_cvt_pk_fp8_f32 v123, v116, v117 op_sel:[0,0,1]
	v_subrev_u32_e32 v120, s38, v120
	v_lshrrev_b32_e32 v252, 2, v120
	v_lshlrev_b32_e32 v253, 4, v120
	v_and_b32_e32 v252, 0xf0, v252
	v_and_b32_e32 v253, 0x300, v253
	v_and_b32_e32 v120, 0xfffffc0f, v120
	v_or3_b32 v120, v120, v252, v253
	v_add_u32_e32 v120, s38, v120
	global_store_dwordx2 v[120:121], v[122:123], off sc1

.LBB0_2211:
	v_mov_b32_e32 v96, v202
	v_mov_b32_e32 v97, v202
	v_pk_mul_f32 v[94:95], v[96:97], v[94:95]
	v_pk_mul_f32 v[92:93], v[202:203], v[92:93]
	v_pk_mul_f32 v[90:91], v[96:97], v[90:91]
	v_pk_mul_f32 v[88:89], v[202:203], v[88:89]
	s_and_b64 vcc, exec, s[12:13]
	s_mov_b64 s[84:85], -1
	s_cbranch_vccnz .LBB0_2218
	s_mov_b64 s[88:89], -1
	s_mov_b64 s[84:85], 0
	s_cmp_lt_i32 s80, 7
	s_mov_b64 s[86:87], 0
	s_cbranch_scc1 .LBB0_2221
	s_cmp_eq_u32 s80, 7
	s_mov_b64 s[86:87], -1
	s_cbranch_scc0 .LBB0_2215
	v_mov_b32_e32 v98, v171
	v_cvt_pk_fp8_f32 v98, v92, v93
	v_mov_b32_e32 v99, v171
	v_cvt_pk_fp8_f32 v99, v88, v89
	v_add_u32_e32 v96, s33, v136
	v_cvt_pk_fp8_f32 v98, v94, v95 op_sel:[0,0,1]
	v_ashrrev_i32_e32 v97, 31, v96
	v_cvt_pk_fp8_f32 v99, v90, v91 op_sel:[0,0,1]
	v_lshlrev_b64 v[96:97], 12, v[96:97]
	v_lshl_add_u64 v[96:97], v[182:183], 0, v[96:97]
	v_subrev_u32_e32 v96, s38, v96
	v_lshrrev_b32_e32 v252, 2, v96
	v_lshlrev_b32_e32 v253, 4, v96
	v_and_b32_e32 v252, 0xf0, v252
	v_and_b32_e32 v253, 0x300, v253
	v_and_b32_e32 v96, 0xfffffc0f, v96
	v_or3_b32 v96, v96, v252, v253
	v_add_u32_e32 v96, s38, v96
	v_lshrrev_b32_e32 v100, 8, v98
	global_store_byte v[96:97], v98, off
	global_store_byte v[96:97], v100, off offset:16
	global_store_byte_d16_hi v[96:97], v98, off offset:32
	v_lshrrev_b32_e32 v98, 24, v98
	global_store_byte v[96:97], v98, off offset:48
	global_store_byte v[96:97], v99, off offset:64
	v_lshrrev_b32_e32 v98, 8, v99
	global_store_byte v[96:97], v98, off offset:80
	global_store_byte_d16_hi v[96:97], v99, off offset:96
	v_lshrrev_b32_e32 v98, 24, v99
	global_store_byte v[96:97], v98, off offset:112
	s_mov_b64 s[86:87], 0

.LBB0_2224:
	v_mov_b32_e32 v98, v171
	v_mov_b32_e32 v99, v171
	v_cvt_pk_fp8_f32 v98, v92, v93
	v_cvt_pk_fp8_f32 v99, v88, v89
	v_lshlrev_b64 v[96:97], 6, v[96:97]
	v_lshl_add_u64 v[96:97], v[184:185], 0, v[96:97]
	v_cvt_pk_fp8_f32 v98, v94, v95 op_sel:[0,0,1]
	v_cvt_pk_fp8_f32 v99, v90, v91 op_sel:[0,0,1]
	v_subrev_u32_e32 v96, s38, v96
	v_lshrrev_b32_e32 v252, 2, v96
	v_lshlrev_b32_e32 v253, 4, v96
	v_and_b32_e32 v252, 0xf0, v252
	v_and_b32_e32 v253, 0x300, v253
	v_and_b32_e32 v96, 0xfffffc0f, v96
	v_or3_b32 v96, v96, v252, v253
	v_add_u32_e32 v96, s38, v96
	global_store_dwordx2 v[96:97], v[98:99], off sc1

.LBB0_2236:
	s_waitcnt lgkmcnt(6)
	v_mov_b32_e32 v108, v202
	s_waitcnt lgkmcnt(4)
	v_mov_b32_e32 v109, v202
	v_pk_mul_f32 v[106:107], v[108:109], v[106:107]
	v_pk_mul_f32 v[104:105], v[202:203], v[104:105]
	v_pk_mul_f32 v[108:109], v[108:109], v[114:115]
	v_pk_mul_f32 v[110:111], v[202:203], v[112:113]
	s_and_b64 vcc, exec, s[12:13]
	s_mov_b64 s[84:85], -1
	s_cbranch_vccnz .LBB0_2248
	s_mov_b64 s[88:89], -1
	s_mov_b64 s[84:85], 0
	s_cmp_lt_i32 s80, 7
	s_mov_b64 s[86:87], 0
	s_cbranch_scc1 .LBB0_2243
	s_cmp_eq_u32 s80, 7
	s_mov_b64 s[86:87], -1
	s_cbranch_scc0 .LBB0_2240
	v_mov_b32_e32 v114, v171
	v_cvt_pk_fp8_f32 v114, v104, v105
	v_mov_b32_e32 v115, v171
	v_cvt_pk_fp8_f32 v115, v110, v111
	v_add_u32_e32 v112, s30, v136
	v_cvt_pk_fp8_f32 v114, v106, v107 op_sel:[0,0,1]
	v_ashrrev_i32_e32 v113, 31, v112
	v_cvt_pk_fp8_f32 v115, v108, v109 op_sel:[0,0,1]
	v_lshlrev_b64 v[112:113], 12, v[112:113]
	v_lshl_add_u64 v[112:113], v[178:179], 0, v[112:113]
	v_subrev_u32_e32 v112, s38, v112
	v_lshrrev_b32_e32 v252, 2, v112
	v_lshlrev_b32_e32 v253, 4, v112
	v_and_b32_e32 v252, 0xf0, v252
	v_and_b32_e32 v253, 0x300, v253
	v_and_b32_e32 v112, 0xfffffc0f, v112
	v_or3_b32 v112, v112, v252, v253
	v_add_u32_e32 v112, s38, v112
	v_lshrrev_b32_e32 v116, 8, v114
	global_store_byte v[112:113], v114, off offset:4
	global_store_byte v[112:113], v116, off offset:20
	global_store_byte_d16_hi v[112:113], v114, off offset:36
	v_lshrrev_b32_e32 v114, 24, v114
	global_store_byte v[112:113], v114, off offset:52
	global_store_byte v[112:113], v115, off offset:68
	v_lshrrev_b32_e32 v114, 8, v115
	global_store_byte v[112:113], v114, off offset:84
	global_store_byte_d16_hi v[112:113], v115, off offset:100
	v_lshrrev_b32_e32 v114, 24, v115
	global_store_byte v[112:113], v114, off offset:116
	s_mov_b64 s[86:87], 0

.LBB0_2246:
	v_mov_b32_e32 v114, v171
	v_mov_b32_e32 v115, v171
	v_cvt_pk_fp8_f32 v114, v104, v105
	v_cvt_pk_fp8_f32 v115, v110, v111
	v_lshlrev_b64 v[112:113], 6, v[112:113]
	v_lshl_add_u64 v[112:113], v[180:181], 0, v[112:113]
	v_cvt_pk_fp8_f32 v114, v106, v107 op_sel:[0,0,1]
	v_cvt_pk_fp8_f32 v115, v108, v109 op_sel:[0,0,1]
	v_subrev_u32_e32 v112, s38, v112
	v_lshrrev_b32_e32 v252, 2, v112
	v_lshlrev_b32_e32 v253, 4, v112
	v_and_b32_e32 v252, 0xf0, v252
	v_and_b32_e32 v253, 0x300, v253
	v_and_b32_e32 v112, 0xfffffc0f, v112
	v_or3_b32 v112, v112, v252, v253
	v_add_u32_e32 v112, s38, v112
	global_store_dwordx2 v[112:113], v[114:115], off sc1

.LBB0_2258:
	s_waitcnt vmcnt(3)
	v_mov_b32_e32 v88, v202
	v_mov_b32_e32 v89, v202
	v_pk_mul_f32 v[86:87], v[88:89], v[86:87]
	v_pk_mul_f32 v[84:85], v[202:203], v[84:85]
	v_pk_mul_f32 v[82:83], v[88:89], v[82:83]
	v_pk_mul_f32 v[80:81], v[202:203], v[80:81]
	s_and_b64 vcc, exec, s[12:13]
	s_mov_b64 s[84:85], -1
	s_cbranch_vccnz .LBB0_2265
	s_mov_b64 s[88:89], -1
	s_mov_b64 s[84:85], 0
	s_cmp_lt_i32 s80, 7
	s_mov_b64 s[86:87], 0
	s_cbranch_scc1 .LBB0_2268
	s_cmp_eq_u32 s80, 7
	s_mov_b64 s[86:87], -1
	s_cbranch_scc0 .LBB0_2262
	v_mov_b32_e32 v90, v171
	v_cvt_pk_fp8_f32 v90, v84, v85
	v_mov_b32_e32 v91, v171
	v_cvt_pk_fp8_f32 v91, v80, v81
	v_add_u32_e32 v88, s33, v136
	v_cvt_pk_fp8_f32 v90, v86, v87 op_sel:[0,0,1]
	v_ashrrev_i32_e32 v89, 31, v88
	v_cvt_pk_fp8_f32 v91, v82, v83 op_sel:[0,0,1]
	v_lshlrev_b64 v[88:89], 12, v[88:89]
	v_lshl_add_u64 v[88:89], v[182:183], 0, v[88:89]
	v_subrev_u32_e32 v88, s38, v88
	v_lshrrev_b32_e32 v252, 2, v88
	v_lshlrev_b32_e32 v253, 4, v88
	v_and_b32_e32 v252, 0xf0, v252
	v_and_b32_e32 v253, 0x300, v253
	v_and_b32_e32 v88, 0xfffffc0f, v88
	v_or3_b32 v88, v88, v252, v253
	v_add_u32_e32 v88, s38, v88
	s_waitcnt vmcnt(1)
	v_lshrrev_b32_e32 v92, 8, v90
	global_store_byte v[88:89], v90, off offset:4
	global_store_byte v[88:89], v92, off offset:20
	global_store_byte_d16_hi v[88:89], v90, off offset:36
	v_lshrrev_b32_e32 v90, 24, v90
	global_store_byte v[88:89], v90, off offset:52
	global_store_byte v[88:89], v91, off offset:68
	v_lshrrev_b32_e32 v90, 8, v91
	global_store_byte v[88:89], v90, off offset:84
	global_store_byte_d16_hi v[88:89], v91, off offset:100
	v_lshrrev_b32_e32 v90, 24, v91
	global_store_byte v[88:89], v90, off offset:116
	s_mov_b64 s[86:87], 0

.LBB0_2271:
	v_mov_b32_e32 v90, v171
	v_mov_b32_e32 v91, v171
	v_cvt_pk_fp8_f32 v90, v84, v85
	v_cvt_pk_fp8_f32 v91, v80, v81
	v_lshlrev_b64 v[88:89], 6, v[88:89]
	v_lshl_add_u64 v[88:89], v[184:185], 0, v[88:89]
	v_cvt_pk_fp8_f32 v90, v86, v87 op_sel:[0,0,1]
	v_cvt_pk_fp8_f32 v91, v82, v83 op_sel:[0,0,1]
	v_subrev_u32_e32 v88, s38, v88
	v_lshrrev_b32_e32 v252, 2, v88
	v_lshlrev_b32_e32 v253, 4, v88
	v_and_b32_e32 v252, 0xf0, v252
	v_and_b32_e32 v253, 0x300, v253
	v_and_b32_e32 v88, 0xfffffc0f, v88
	v_or3_b32 v88, v88, v252, v253
	v_add_u32_e32 v88, s38, v88
	global_store_dwordx2 v[88:89], v[90:91], off sc1

.LBB0_2283:
	s_waitcnt vmcnt(0) lgkmcnt(6)
	v_mov_b32_e32 v100, v202
	s_waitcnt lgkmcnt(4)
	v_mov_b32_e32 v101, v202
	v_pk_mul_f32 v[98:99], v[100:101], v[98:99]
	v_pk_mul_f32 v[96:97], v[202:203], v[96:97]
	v_pk_mul_f32 v[100:101], v[100:101], v[106:107]
	v_pk_mul_f32 v[102:103], v[202:203], v[104:105]
	s_and_b64 vcc, exec, s[12:13]
	s_mov_b64 s[84:85], -1
	s_cbranch_vccnz .LBB0_2295
	s_mov_b64 s[88:89], -1
	s_mov_b64 s[84:85], 0
	s_cmp_lt_i32 s80, 7
	s_mov_b64 s[86:87], 0
	s_cbranch_scc1 .LBB0_2290
	s_cmp_eq_u32 s80, 7
	s_mov_b64 s[86:87], -1
	s_cbranch_scc0 .LBB0_2287
	v_mov_b32_e32 v106, v171
	v_cvt_pk_fp8_f32 v106, v96, v97
	v_mov_b32_e32 v107, v171
	v_cvt_pk_fp8_f32 v107, v102, v103
	v_add_u32_e32 v104, s30, v136
	v_cvt_pk_fp8_f32 v106, v98, v99 op_sel:[0,0,1]
	v_ashrrev_i32_e32 v105, 31, v104
	v_cvt_pk_fp8_f32 v107, v100, v101 op_sel:[0,0,1]
	v_lshlrev_b64 v[104:105], 12, v[104:105]
	v_lshl_add_u64 v[104:105], v[178:179], 0, v[104:105]
	v_subrev_u32_e32 v104, s38, v104
	v_lshrrev_b32_e32 v252, 2, v104
	v_lshlrev_b32_e32 v253, 4, v104
	v_and_b32_e32 v252, 0xf0, v252
	v_and_b32_e32 v253, 0x300, v253
	v_and_b32_e32 v104, 0xfffffc0f, v104
	v_or3_b32 v104, v104, v252, v253
	v_add_u32_e32 v104, s38, v104
	v_lshrrev_b32_e32 v108, 8, v106
	global_store_byte v[104:105], v106, off offset:8
	global_store_byte v[104:105], v108, off offset:24
	global_store_byte_d16_hi v[104:105], v106, off offset:40
	v_lshrrev_b32_e32 v106, 24, v106
	global_store_byte v[104:105], v106, off offset:56
	global_store_byte v[104:105], v107, off offset:72
	v_lshrrev_b32_e32 v106, 8, v107
	global_store_byte v[104:105], v106, off offset:88
	global_store_byte_d16_hi v[104:105], v107, off offset:104
	v_lshrrev_b32_e32 v106, 24, v107
	global_store_byte v[104:105], v106, off offset:120
	s_mov_b64 s[86:87], 0

.LBB0_2293:
	v_mov_b32_e32 v106, v171
	v_mov_b32_e32 v107, v171
	v_cvt_pk_fp8_f32 v106, v96, v97
	v_cvt_pk_fp8_f32 v107, v102, v103
	v_lshlrev_b64 v[104:105], 6, v[104:105]
	v_lshl_add_u64 v[104:105], v[180:181], 0, v[104:105]
	v_cvt_pk_fp8_f32 v106, v98, v99 op_sel:[0,0,1]
	v_cvt_pk_fp8_f32 v107, v100, v101 op_sel:[0,0,1]
	v_subrev_u32_e32 v104, s38, v104
	v_lshrrev_b32_e32 v252, 2, v104
	v_lshlrev_b32_e32 v253, 4, v104
	v_and_b32_e32 v252, 0xf0, v252
	v_and_b32_e32 v253, 0x300, v253
	v_and_b32_e32 v104, 0xfffffc0f, v104
	v_or3_b32 v104, v104, v252, v253
	v_add_u32_e32 v104, s38, v104
	global_store_dwordx2 v[104:105], v[106:107], off sc1

.LBB0_2305:
	v_mov_b32_e32 v80, v202
	v_mov_b32_e32 v81, v202
	v_pk_mul_f32 v[78:79], v[80:81], v[78:79]
	v_pk_mul_f32 v[76:77], v[202:203], v[76:77]
	v_pk_mul_f32 v[74:75], v[80:81], v[74:75]
	v_pk_mul_f32 v[72:73], v[202:203], v[72:73]
	s_and_b64 vcc, exec, s[12:13]
	s_mov_b64 s[84:85], -1
	s_cbranch_vccnz .LBB0_2312
	s_mov_b64 s[88:89], -1
	s_mov_b64 s[84:85], 0
	s_cmp_lt_i32 s80, 7
	s_mov_b64 s[86:87], 0
	s_cbranch_scc1 .LBB0_2315
	s_cmp_eq_u32 s80, 7
	s_mov_b64 s[86:87], -1
	s_cbranch_scc0 .LBB0_2309
	v_mov_b32_e32 v82, v171
	v_cvt_pk_fp8_f32 v82, v76, v77
	v_mov_b32_e32 v83, v171
	v_cvt_pk_fp8_f32 v83, v72, v73
	v_add_u32_e32 v80, s33, v136
	v_cvt_pk_fp8_f32 v82, v78, v79 op_sel:[0,0,1]
	v_ashrrev_i32_e32 v81, 31, v80
	v_cvt_pk_fp8_f32 v83, v74, v75 op_sel:[0,0,1]
	v_lshlrev_b64 v[80:81], 12, v[80:81]
	v_lshl_add_u64 v[80:81], v[182:183], 0, v[80:81]
	v_subrev_u32_e32 v80, s38, v80
	v_lshrrev_b32_e32 v252, 2, v80
	v_lshlrev_b32_e32 v253, 4, v80
	v_and_b32_e32 v252, 0xf0, v252
	v_and_b32_e32 v253, 0x300, v253
	v_and_b32_e32 v80, 0xfffffc0f, v80
	v_or3_b32 v80, v80, v252, v253
	v_add_u32_e32 v80, s38, v80
	v_lshrrev_b32_e32 v84, 8, v82
	global_store_byte v[80:81], v82, off offset:8
	global_store_byte v[80:81], v84, off offset:24
	global_store_byte_d16_hi v[80:81], v82, off offset:40
	v_lshrrev_b32_e32 v82, 24, v82
	global_store_byte v[80:81], v82, off offset:56
	global_store_byte v[80:81], v83, off offset:72
	v_lshrrev_b32_e32 v82, 8, v83
	global_store_byte v[80:81], v82, off offset:88
	global_store_byte_d16_hi v[80:81], v83, off offset:104
	v_lshrrev_b32_e32 v82, 24, v83
	global_store_byte v[80:81], v82, off offset:120
	s_mov_b64 s[86:87], 0

.LBB0_2318:
	v_mov_b32_e32 v82, v171
	v_mov_b32_e32 v83, v171
	v_cvt_pk_fp8_f32 v82, v76, v77
	v_cvt_pk_fp8_f32 v83, v72, v73
	v_lshlrev_b64 v[80:81], 6, v[80:81]
	v_lshl_add_u64 v[80:81], v[184:185], 0, v[80:81]
	v_cvt_pk_fp8_f32 v82, v78, v79 op_sel:[0,0,1]
	v_cvt_pk_fp8_f32 v83, v74, v75 op_sel:[0,0,1]
	v_subrev_u32_e32 v80, s38, v80
	v_lshrrev_b32_e32 v252, 2, v80
	v_lshlrev_b32_e32 v253, 4, v80
	v_and_b32_e32 v252, 0xf0, v252
	v_and_b32_e32 v253, 0x300, v253
	v_and_b32_e32 v80, 0xfffffc0f, v80
	v_or3_b32 v80, v80, v252, v253
	v_add_u32_e32 v80, s38, v80
	global_store_dwordx2 v[80:81], v[82:83], off sc1

.LBB0_2330:
	s_waitcnt lgkmcnt(6)
	v_mov_b32_e32 v92, v202
	s_waitcnt lgkmcnt(4)
	v_mov_b32_e32 v93, v202
	v_pk_mul_f32 v[90:91], v[92:93], v[90:91]
	v_pk_mul_f32 v[88:89], v[202:203], v[88:89]
	v_pk_mul_f32 v[92:93], v[92:93], v[98:99]
	v_pk_mul_f32 v[94:95], v[202:203], v[96:97]
	s_and_b64 vcc, exec, s[12:13]
	s_mov_b64 s[84:85], -1
	s_cbranch_vccnz .LBB0_2342
	s_mov_b64 s[88:89], -1
	s_mov_b64 s[84:85], 0
	s_cmp_lt_i32 s80, 7
	s_mov_b64 s[86:87], 0
	s_cbranch_scc1 .LBB0_2337
	s_cmp_eq_u32 s80, 7
	s_mov_b64 s[86:87], -1
	s_cbranch_scc0 .LBB0_2334
	v_mov_b32_e32 v98, v171
	v_cvt_pk_fp8_f32 v98, v88, v89
	v_mov_b32_e32 v99, v171
	v_cvt_pk_fp8_f32 v99, v94, v95
	v_add_u32_e32 v96, s30, v136
	v_cvt_pk_fp8_f32 v98, v90, v91 op_sel:[0,0,1]
	v_ashrrev_i32_e32 v97, 31, v96
	v_cvt_pk_fp8_f32 v99, v92, v93 op_sel:[0,0,1]
	v_lshlrev_b64 v[96:97], 12, v[96:97]
	v_lshl_add_u64 v[96:97], v[186:187], 0, v[96:97]
	v_subrev_u32_e32 v96, s38, v96
	v_lshrrev_b32_e32 v252, 2, v96
	v_lshlrev_b32_e32 v253, 4, v96
	v_and_b32_e32 v252, 0xf0, v252
	v_and_b32_e32 v253, 0x300, v253
	v_and_b32_e32 v96, 0xfffffc0f, v96
	v_or3_b32 v96, v96, v252, v253
	v_add_u32_e32 v96, s38, v96
	v_lshrrev_b32_e32 v100, 8, v98
	global_store_byte v[96:97], v98, off
	global_store_byte v[96:97], v100, off offset:16
	global_store_byte_d16_hi v[96:97], v98, off offset:32
	v_lshrrev_b32_e32 v98, 24, v98
	global_store_byte v[96:97], v98, off offset:48
	global_store_byte v[96:97], v99, off offset:64
	v_lshrrev_b32_e32 v98, 8, v99
	global_store_byte v[96:97], v98, off offset:80
	global_store_byte_d16_hi v[96:97], v99, off offset:96
	v_lshrrev_b32_e32 v98, 24, v99
	global_store_byte v[96:97], v98, off offset:112
	s_mov_b64 s[86:87], 0

.LBB0_2340:
	v_mov_b32_e32 v98, v171
	v_mov_b32_e32 v99, v171
	v_cvt_pk_fp8_f32 v98, v88, v89
	v_cvt_pk_fp8_f32 v99, v94, v95
	v_lshlrev_b64 v[96:97], 6, v[96:97]
	v_lshl_add_u64 v[96:97], v[180:181], 0, v[96:97]
	v_cvt_pk_fp8_f32 v98, v90, v91 op_sel:[0,0,1]
	v_cvt_pk_fp8_f32 v99, v92, v93 op_sel:[0,0,1]
	v_subrev_u32_e32 v96, s38, v96
	v_lshrrev_b32_e32 v252, 2, v96
	v_lshlrev_b32_e32 v253, 4, v96
	v_and_b32_e32 v252, 0xf0, v252
	v_and_b32_e32 v253, 0x300, v253
	v_and_b32_e32 v96, 0xfffffc0f, v96
	v_or3_b32 v96, v96, v252, v253
	v_add_u32_e32 v96, s38, v96
	global_store_dwordx2 v[96:97], v[98:99], off sc1

.LBB0_2352:
	s_waitcnt vmcnt(3)
	v_mov_b32_e32 v72, v202
	v_mov_b32_e32 v73, v202
	v_pk_mul_f32 v[70:71], v[72:73], v[70:71]
	v_pk_mul_f32 v[68:69], v[202:203], v[68:69]
	v_pk_mul_f32 v[66:67], v[72:73], v[66:67]
	v_pk_mul_f32 v[64:65], v[202:203], v[64:65]
	s_and_b64 vcc, exec, s[12:13]
	s_mov_b64 s[10:11], -1
	s_cbranch_vccnz .LBB0_2364
	s_mov_b64 s[82:83], -1
	s_mov_b64 s[10:11], 0
	s_cmp_lt_i32 s80, 7
	s_mov_b64 s[12:13], 0
	s_cbranch_scc1 .LBB0_2359
	s_cmp_eq_u32 s80, 7
	s_mov_b64 s[12:13], -1
	s_cbranch_scc0 .LBB0_2356
	v_mov_b32_e32 v74, v171
	v_cvt_pk_fp8_f32 v74, v68, v69
	v_mov_b32_e32 v75, v171
	v_cvt_pk_fp8_f32 v75, v64, v65
	v_add_u32_e32 v72, s33, v136
	v_cvt_pk_fp8_f32 v74, v70, v71 op_sel:[0,0,1]
	v_ashrrev_i32_e32 v73, 31, v72
	v_cvt_pk_fp8_f32 v75, v66, v67 op_sel:[0,0,1]
	v_lshlrev_b64 v[72:73], 12, v[72:73]
	v_lshl_add_u64 v[72:73], v[188:189], 0, v[72:73]
	v_subrev_u32_e32 v72, s38, v72
	v_lshrrev_b32_e32 v252, 2, v72
	v_lshlrev_b32_e32 v253, 4, v72
	v_and_b32_e32 v252, 0xf0, v252
	v_and_b32_e32 v253, 0x300, v253
	v_and_b32_e32 v72, 0xfffffc0f, v72
	v_or3_b32 v72, v72, v252, v253
	v_add_u32_e32 v72, s38, v72
	s_waitcnt vmcnt(1)
	v_lshrrev_b32_e32 v76, 8, v74
	global_store_byte v[72:73], v74, off
	global_store_byte v[72:73], v76, off offset:16
	global_store_byte_d16_hi v[72:73], v74, off offset:32
	v_lshrrev_b32_e32 v74, 24, v74
	global_store_byte v[72:73], v74, off offset:48
	global_store_byte v[72:73], v75, off offset:64
	v_lshrrev_b32_e32 v74, 8, v75
	global_store_byte v[72:73], v74, off offset:80
	global_store_byte_d16_hi v[72:73], v75, off offset:96
	v_lshrrev_b32_e32 v74, 24, v75
	global_store_byte v[72:73], v74, off offset:112
	s_mov_b64 s[12:13], 0

.LBB0_2362:
	v_mov_b32_e32 v74, v171
	v_mov_b32_e32 v75, v171
	v_cvt_pk_fp8_f32 v74, v68, v69
	v_cvt_pk_fp8_f32 v75, v64, v65
	v_lshlrev_b64 v[72:73], 6, v[72:73]
	v_lshl_add_u64 v[72:73], v[184:185], 0, v[72:73]
	v_cvt_pk_fp8_f32 v74, v70, v71 op_sel:[0,0,1]
	v_cvt_pk_fp8_f32 v75, v66, v67 op_sel:[0,0,1]
	v_subrev_u32_e32 v72, s38, v72
	v_lshrrev_b32_e32 v252, 2, v72
	v_lshlrev_b32_e32 v253, 4, v72
	v_and_b32_e32 v252, 0xf0, v252
	v_and_b32_e32 v253, 0x300, v253
	v_and_b32_e32 v72, 0xfffffc0f, v72
	v_or3_b32 v72, v72, v252, v253
	v_add_u32_e32 v72, s38, v72
	global_store_dwordx2 v[72:73], v[74:75], off sc1
